# attn_c softmax: packed f32 adds of the row-sum replaced by scalar v_add_f32 (packed f32 VALU is slow beside the partner wave's MFMAs)
# baseline (speedup 1.0000x reference)
; #define MFMA16(a, b, c) __builtin_amdgcn_mfma_f32_16x16x32_bf16((a), (b), (c), 0, 0, 0)
; DI void attn_c_item(const Params& P, int l, int b, int h, int qb, char* shm, float B2, int dry) {
;     ...
;   for (int kt = 0; kt < ntile; ++kt) {
;     const int cur = kt & 1;
;     if (kt + 1 < ntile) A_STAGE(cur ^ 1, kt + 1);
;     if (kt <= my_last) {
;       const char* Kb = shm + cur * BUF_B;
;       const char* Vb = Kb + KT_B;
;       f32x4 s[4][2];
; #pragma unroll
;       for (int i = 0; i < 4; ++i) { s[i][0] = f32x4{0.f, 0.f, 0.f, 0.f}; s[i][1] = f32x4{0.f, 0.f, 0.f, 0.f}; }
;       const char* Kf = Kb + lds_byte<6>(fr, fq * 8);
;       const char* Vf = Vb + lds_byte<2>(fr, fq * 8);
;       bf16x8 kf[2][4], vf0[8], vf1[8];
; #pragma unroll
;       for (int sub = 0; sub < 4; ++sub) kf[0][sub] = *(const bf16x8*)(Kf + sub * 6144);
; #pragma unroll
;       for (int ks = 0; ks < 6; ++ks) {
;         if (ks < 5) {
; #pragma unroll
;           for (int sub = 0; sub < 4; ++sub) kf[(ks + 1) & 1][sub] = *(const bf16x8*)(Kf + sub * 6144 + (ks + 1) * 1024);
;         } else {
; #pragma unroll
;           for (int dvs = 0; dvs < 8; ++dvs) vf0[dvs] = *(const bf16x8*)(Vf + dvs * 2048);
;         }
; #pragma unroll
;         for (int sub = 0; sub < 4; ++sub) {
;           s[sub][0] = MFMA16(kf[ks & 1][sub], qf[0][ks], s[sub][0]);
;           s[sub][1] = MFMA16(kf[ks & 1][sub], qf[1][ks], s[sub][1]);
;         }
;       }
;       __builtin_amdgcn_sched_group_barrier(0x100, 4, 0);
; #pragma unroll
;       for (int i = 0; i < 20; ++i) { __builtin_amdgcn_sched_group_barrier(0x100, 1, 0); __builtin_amdgcn_sched_group_barrier(0x008, 2, 0); }
; #pragma unroll
;       for (int i = 0; i < 4; ++i) { __builtin_amdgcn_sched_group_barrier(0x100, 2, 0); __builtin_amdgcn_sched_group_barrier(0x008, 2, 0); }
;       __builtin_amdgcn_sched_barrier(0);
.LBB0_578:
	s_cmp_gt_i32 s36, s1
	s_cbranch_scc1 .LBB0_580
	s_mul_i32 s37, s37, 0xa000
	v_or_b32_e32 v127, s37, v121
	ds_read_b128 v[128:131], v127
	ds_read_b128 v[136:139], v127 offset:6144
	ds_read_b128 v[140:143], v127 offset:12288
	ds_read_b128 v[144:147], v127 offset:18432
	ds_read_b128 v[148:151], v127 offset:1024
	s_waitcnt lgkmcnt(4)
	v_mfma_f32_16x16x32_bf16 v[152:155], v[128:131], v[68:71], v[232:235]
	v_mfma_f32_16x16x32_bf16 v[128:131], v[128:131], v[76:79], v[232:235]
	ds_read_b128 v[156:159], v127 offset:7168
	s_waitcnt lgkmcnt(4)
	v_mfma_f32_16x16x32_bf16 v[160:163], v[136:139], v[68:71], v[232:235]
	v_mfma_f32_16x16x32_bf16 v[136:139], v[136:139], v[76:79], v[232:235]
	ds_read_b128 v[164:167], v127 offset:13312
	s_waitcnt lgkmcnt(4)
	v_mfma_f32_16x16x32_bf16 v[168:171], v[140:143], v[68:71], v[232:235]
	v_mfma_f32_16x16x32_bf16 v[140:143], v[140:143], v[76:79], v[232:235]
	ds_read_b128 v[172:175], v127 offset:19456
	s_waitcnt lgkmcnt(4)
	v_mfma_f32_16x16x32_bf16 v[176:179], v[144:147], v[68:71], v[232:235]
	v_mfma_f32_16x16x32_bf16 v[144:147], v[144:147], v[76:79], v[232:235]
	ds_read_b128 v[180:183], v127 offset:2048
	s_waitcnt lgkmcnt(4)
	v_mfma_f32_16x16x32_bf16 v[152:155], v[148:151], v[60:63], v[152:155]
	v_mfma_f32_16x16x32_bf16 v[128:131], v[148:151], v[80:83], v[128:131]
	ds_read_b128 v[148:151], v127 offset:8192
	s_waitcnt lgkmcnt(4)
	v_mfma_f32_16x16x32_bf16 v[160:163], v[156:159], v[60:63], v[160:163]
	v_mfma_f32_16x16x32_bf16 v[136:139], v[156:159], v[80:83], v[136:139]
	ds_read_b128 v[156:159], v127 offset:14336
	s_waitcnt lgkmcnt(4)
	v_mfma_f32_16x16x32_bf16 v[168:171], v[164:167], v[60:63], v[168:171]
	v_mfma_f32_16x16x32_bf16 v[140:143], v[164:167], v[80:83], v[140:143]
	ds_read_b128 v[164:167], v127 offset:20480
	s_waitcnt lgkmcnt(4)
	v_mfma_f32_16x16x32_bf16 v[176:179], v[172:175], v[60:63], v[176:179]
	v_mfma_f32_16x16x32_bf16 v[144:147], v[172:175], v[80:83], v[144:147]
	ds_read_b128 v[172:175], v127 offset:3072
	s_waitcnt lgkmcnt(4)
	v_mfma_f32_16x16x32_bf16 v[152:155], v[180:183], v[56:59], v[152:155]
	v_mfma_f32_16x16x32_bf16 v[128:131], v[180:183], v[84:87], v[128:131]
	ds_read_b128 v[180:183], v127 offset:9216
	s_waitcnt lgkmcnt(4)
	v_mfma_f32_16x16x32_bf16 v[160:163], v[148:151], v[56:59], v[160:163]
	v_mfma_f32_16x16x32_bf16 v[136:139], v[148:151], v[84:87], v[136:139]
	ds_read_b128 v[148:151], v127 offset:15360
	s_waitcnt lgkmcnt(4)
	v_mfma_f32_16x16x32_bf16 v[168:171], v[156:159], v[56:59], v[168:171]
	v_mfma_f32_16x16x32_bf16 v[140:143], v[156:159], v[84:87], v[140:143]
	ds_read_b128 v[156:159], v127 offset:21504
	s_waitcnt lgkmcnt(4)
	v_mfma_f32_16x16x32_bf16 v[176:179], v[164:167], v[56:59], v[176:179]
	v_mfma_f32_16x16x32_bf16 v[144:147], v[164:167], v[84:87], v[144:147]
	ds_read_b128 v[164:167], v127 offset:4096
	s_waitcnt lgkmcnt(4)
	v_mfma_f32_16x16x32_bf16 v[152:155], v[172:175], v[44:47], v[152:155]
	v_mfma_f32_16x16x32_bf16 v[128:131], v[172:175], v[88:91], v[128:131]
	ds_read_b128 v[172:175], v127 offset:10240
	s_waitcnt lgkmcnt(4)
	v_mfma_f32_16x16x32_bf16 v[160:163], v[180:183], v[44:47], v[160:163]
	v_mfma_f32_16x16x32_bf16 v[136:139], v[180:183], v[88:91], v[136:139]
	ds_read_b128 v[180:183], v127 offset:16384
	s_waitcnt lgkmcnt(4)
	v_mfma_f32_16x16x32_bf16 v[168:171], v[148:151], v[44:47], v[168:171]
	v_mfma_f32_16x16x32_bf16 v[140:143], v[148:151], v[88:91], v[140:143]
	ds_read_b128 v[148:151], v127 offset:22528
	s_waitcnt lgkmcnt(4)
	v_mfma_f32_16x16x32_bf16 v[176:179], v[156:159], v[44:47], v[176:179]
	v_mfma_f32_16x16x32_bf16 v[144:147], v[156:159], v[88:91], v[144:147]
	ds_read_b128 v[156:159], v127 offset:5120
	s_waitcnt lgkmcnt(4)
	v_mfma_f32_16x16x32_bf16 v[152:155], v[164:167], v[32:35], v[152:155]
	v_mfma_f32_16x16x32_bf16 v[128:131], v[164:167], v[100:103], v[128:131]
	ds_read_b128 v[164:167], v127 offset:11264
	s_waitcnt lgkmcnt(4)
	v_mfma_f32_16x16x32_bf16 v[160:163], v[172:175], v[32:35], v[160:163]
	v_mfma_f32_16x16x32_bf16 v[136:139], v[172:175], v[100:103], v[136:139]
	ds_read_b128 v[172:175], v127 offset:17408
	s_waitcnt lgkmcnt(4)
	v_mfma_f32_16x16x32_bf16 v[168:171], v[180:183], v[32:35], v[168:171]
	v_mfma_f32_16x16x32_bf16 v[140:143], v[180:183], v[100:103], v[140:143]
	ds_read_b128 v[180:183], v127 offset:23552
	s_waitcnt lgkmcnt(4)
	v_mfma_f32_16x16x32_bf16 v[176:179], v[148:151], v[32:35], v[176:179]
	v_mfma_f32_16x16x32_bf16 v[144:147], v[148:151], v[100:103], v[144:147]
	ds_read_b128 v[148:151], v127 offset:38912
	ds_read_b128 v[184:187], v127 offset:36864
	s_waitcnt lgkmcnt(5)
	v_mfma_f32_16x16x32_bf16 v[152:155], v[156:159], v[36:39], v[152:155]
	v_mfma_f32_16x16x32_bf16 v[128:131], v[156:159], v[108:111], v[128:131]
	ds_read_b128 v[156:159], v127 offset:34816
	ds_read_b128 v[188:191], v127 offset:32768
	s_waitcnt lgkmcnt(6)
	v_mfma_f32_16x16x32_bf16 v[160:163], v[164:167], v[36:39], v[160:163]
	v_mfma_f32_16x16x32_bf16 v[136:139], v[164:167], v[108:111], v[136:139]
	ds_read_b128 v[164:167], v127 offset:30720
	ds_read_b128 v[192:195], v127 offset:28672
	s_waitcnt lgkmcnt(7)
	v_mfma_f32_16x16x32_bf16 v[168:171], v[172:175], v[36:39], v[168:171]
	v_mfma_f32_16x16x32_bf16 v[140:143], v[172:175], v[108:111], v[140:143]
	ds_read_b128 v[172:175], v127 offset:26624
	ds_read_b128 v[196:199], v127 offset:24576
	s_waitcnt lgkmcnt(8)
; #define MFMA16(a, b, c) __builtin_amdgcn_mfma_f32_16x16x32_bf16((a), (b), (c), 0, 0, 0)
; DI void attn_c_item(const Params& P, int l, int b, int h, int qb, char* shm, float B2, int dry) {
;     ...
;       bf16x8 pf[2][2];
; #pragma unroll
;       for (int qs = 0; qs < 2; ++qs) {
; #pragma unroll
;         for (int kk = 0; kk < 2; ++kk) {
;           float pv[8];
; #pragma unroll
;           for (int j = 0; j < 4; ++j) {
;             pv[j] = __builtin_amdgcn_exp2f(s[2 * kk][qs][j] - B2);
;             pv[4 + j] = __builtin_amdgcn_exp2f(s[2 * kk + 1][qs][j] - B2);
;           }
;           lsum[qs] += ((pv[0] + pv[1]) + (pv[2] + pv[3])) + ((pv[4] + pv[5]) + (pv[6] + pv[7]));
;           i32x4 pk;
; #pragma unroll
;           for (int e = 0; e < 4; ++e) pk[e] = (int)pack2(pv[2 * e], pv[2 * e + 1]);
;           pf[kk][qs] = __builtin_bit_cast(bf16x8, pk);
;         }
;       }
;       __builtin_amdgcn_sched_barrier(0);
; #pragma unroll
;       for (int dvs = 0; dvs < 8; ++dvs) vf1[dvs] = *(const bf16x8*)(Vf + dvs * 2048 + 1024);
; #pragma unroll
;       for (int dvs = 0; dvs < 8; ++dvs) {
;         o[dvs][0] = MFMA16(vf0[dvs], pf[0][0], o[dvs][0]);
;         o[dvs][1] = MFMA16(vf0[dvs], pf[0][1], o[dvs][1]);
;       }
; #pragma unroll
;       for (int dvs = 0; dvs < 8; ++dvs) {
;         o[dvs][0] = MFMA16(vf1[dvs], pf[1][0], o[dvs][0]);
;         o[dvs][1] = MFMA16(vf1[dvs], pf[1][1], o[dvs][1]);
;       }
; #pragma unroll
;       for (int i = 0; i < 8; ++i) { __builtin_amdgcn_sched_group_barrier(0x100, 1, 0); __builtin_amdgcn_sched_group_barrier(0x008, 2, 0); }
;       __builtin_amdgcn_sched_group_barrier(0x008, 16, 0);
;       __builtin_amdgcn_sched_barrier(0);
	v_mfma_f32_16x16x32_bf16 v[176:179], v[180:183], v[36:39], v[176:179]
	v_mfma_f32_16x16x32_bf16 v[144:147], v[180:183], v[108:111], v[144:147]
	v_exp_f32_e32 v181, v152
	v_exp_f32_e32 v180, v128
	v_exp_f32_e32 v183, v160
	v_exp_f32_e32 v182, v136
	v_exp_f32_e32 v153, v153
	v_exp_f32_e32 v152, v129
	v_exp_f32_e32 v161, v161
	v_exp_f32_e32 v160, v137
	v_exp_f32_e32 v201, v154
	v_exp_f32_e32 v200, v130
	v_exp_f32_e32 v219, v162
	v_exp_f32_e32 v218, v138
	v_exp_f32_e32 v155, v155
	v_exp_f32_e32 v154, v131
	v_exp_f32_e32 v163, v163
	v_exp_f32_e32 v162, v139
	v_exp_f32_e32 v221, v168
	v_exp_f32_e32 v220, v140
	v_exp_f32_e32 v223, v176
	v_exp_f32_e32 v222, v144
	v_exp_f32_e32 v169, v169
	v_exp_f32_e32 v168, v141
	v_exp_f32_e32 v177, v177
	v_exp_f32_e32 v176, v145
	v_exp_f32_e32 v225, v170
	v_exp_f32_e32 v224, v142
	v_exp_f32_e32 v227, v178
	v_exp_f32_e32 v226, v146
	v_exp_f32_e32 v171, v171
	v_exp_f32_e32 v170, v143
	v_add_f32_e32 v140, v180, v152
	v_add_f32_e32 v141, v181, v153
	v_add_f32_e32 v142, v200, v154
	v_add_f32_e32 v143, v201, v155
	v_exp_f32_e32 v179, v179
	v_exp_f32_e32 v178, v147
	v_add_f32_e32 v140, v140, v142
	v_add_f32_e32 v141, v141, v143
	v_add_f32_e32 v142, v182, v160
	v_add_f32_e32 v143, v183, v161
	v_add_f32_e32 v144, v218, v162
	v_add_f32_e32 v145, v219, v163
	v_cvt_pk_bf16_f32 v128, v181, v153
	v_add_f32_e32 v142, v142, v144
	v_add_f32_e32 v143, v143, v145
	v_add_f32_e32 v144, v226, v178
	v_add_f32_e32 v145, v227, v179
	v_add_f32_e32 v140, v140, v142
	v_add_f32_e32 v141, v141, v143
	v_add_f32_e32 v142, v224, v170
	v_add_f32_e32 v143, v225, v171
	v_add_f32_e32 v118, v118, v140
	v_add_f32_e32 v119, v119, v141
	v_add_f32_e32 v140, v220, v168
	v_add_f32_e32 v141, v221, v169
	v_cvt_pk_bf16_f32 v129, v201, v155
	v_add_f32_e32 v140, v140, v142
	v_add_f32_e32 v141, v141, v143
	v_add_f32_e32 v142, v222, v176
	v_add_f32_e32 v143, v223, v177
	v_cvt_pk_bf16_f32 v130, v183, v161
	v_add_f32_e32 v142, v142, v144
	v_add_f32_e32 v143, v143, v145
	v_cvt_pk_bf16_f32 v131, v219, v163
	v_add_f32_e32 v228, v140, v142
	v_add_f32_e32 v229, v141, v143
	v_cvt_pk_bf16_f32 v136, v221, v169
	v_add_f32_e32 v118, v118, v228
	v_add_f32_e32 v119, v119, v229
	v_cvt_pk_bf16_f32 v137, v225, v171
	v_cvt_pk_bf16_f32 v138, v223, v177
	v_cvt_pk_bf16_f32 v139, v227, v179
	v_cvt_pk_bf16_f32 v140, v180, v152
	v_cvt_pk_bf16_f32 v141, v200, v154
	v_cvt_pk_bf16_f32 v142, v182, v160
	v_cvt_pk_bf16_f32 v143, v218, v162
	v_cvt_pk_bf16_f32 v144, v220, v168
	v_cvt_pk_bf16_f32 v145, v224, v170
	v_cvt_pk_bf16_f32 v146, v222, v176
	v_cvt_pk_bf16_f32 v147, v226, v178
	ds_read_b128 v[152:155], v127 offset:25600
	s_waitcnt lgkmcnt(1)
	v_mfma_f32_16x16x32_bf16 v[104:107], v[196:199], v[128:131], v[104:107]
	v_mfma_f32_16x16x32_bf16 v[28:31], v[196:199], v[140:143], v[28:31]
	ds_read_b128 v[160:163], v127 offset:27648
	v_mfma_f32_16x16x32_bf16 v[96:99], v[172:175], v[128:131], v[96:99]
	v_mfma_f32_16x16x32_bf16 v[24:27], v[172:175], v[140:143], v[24:27]
	ds_read_b128 v[168:171], v127 offset:29696
	v_mfma_f32_16x16x32_bf16 v[92:95], v[192:195], v[128:131], v[92:95]
	v_mfma_f32_16x16x32_bf16 v[20:23], v[192:195], v[140:143], v[20:23]
	ds_read_b128 v[172:175], v127 offset:31744
	v_mfma_f32_16x16x32_bf16 v[72:75], v[164:167], v[128:131], v[72:75]
	v_mfma_f32_16x16x32_bf16 v[16:19], v[164:167], v[140:143], v[16:19]
	ds_read_b128 v[164:167], v127 offset:33792
	v_mfma_f32_16x16x32_bf16 v[64:67], v[188:191], v[128:131], v[64:67]
	v_mfma_f32_16x16x32_bf16 v[12:15], v[188:191], v[140:143], v[12:15]
	ds_read_b128 v[176:179], v127 offset:35840
	v_mfma_f32_16x16x32_bf16 v[52:55], v[156:159], v[128:131], v[52:55]
	v_mfma_f32_16x16x32_bf16 v[8:11], v[156:159], v[140:143], v[8:11]
	ds_read_b128 v[156:159], v127 offset:37888
	v_mfma_f32_16x16x32_bf16 v[48:51], v[184:187], v[128:131], v[48:51]
	v_mfma_f32_16x16x32_bf16 v[4:7], v[184:187], v[140:143], v[4:7]
	ds_read_b128 v[180:183], v127 offset:39936
	v_mfma_f32_16x16x32_bf16 v[40:43], v[148:151], v[128:131], v[40:43]
	v_mfma_f32_16x16x32_bf16 v[0:3], v[148:151], v[140:143], v[0:3]
	s_waitcnt lgkmcnt(7)
	v_mfma_f32_16x16x32_bf16 v[104:107], v[152:155], v[136:139], v[104:107]
	v_mfma_f32_16x16x32_bf16 v[28:31], v[152:155], v[144:147], v[28:31]
	s_waitcnt lgkmcnt(6)
	v_mfma_f32_16x16x32_bf16 v[96:99], v[160:163], v[136:139], v[96:99]
	v_mfma_f32_16x16x32_bf16 v[24:27], v[160:163], v[144:147], v[24:27]
	s_waitcnt lgkmcnt(5)
	v_mfma_f32_16x16x32_bf16 v[92:95], v[168:171], v[136:139], v[92:95]
	v_mfma_f32_16x16x32_bf16 v[20:23], v[168:171], v[144:147], v[20:23]
	s_waitcnt lgkmcnt(4)
	v_mfma_f32_16x16x32_bf16 v[72:75], v[172:175], v[136:139], v[72:75]
	v_mfma_f32_16x16x32_bf16 v[16:19], v[172:175], v[144:147], v[16:19]
	s_waitcnt lgkmcnt(3)
	v_mfma_f32_16x16x32_bf16 v[64:67], v[164:167], v[136:139], v[64:67]
	v_mfma_f32_16x16x32_bf16 v[12:15], v[164:167], v[144:147], v[12:15]
	s_waitcnt lgkmcnt(2)
	v_mfma_f32_16x16x32_bf16 v[52:55], v[176:179], v[136:139], v[52:55]
	v_mfma_f32_16x16x32_bf16 v[8:11], v[176:179], v[144:147], v[8:11]
	s_waitcnt lgkmcnt(1)
	v_mfma_f32_16x16x32_bf16 v[48:51], v[156:159], v[136:139], v[48:51]
	v_mfma_f32_16x16x32_bf16 v[4:7], v[156:159], v[144:147], v[4:7]
	s_waitcnt lgkmcnt(0)
	v_mfma_f32_16x16x32_bf16 v[40:43], v[180:183], v[136:139], v[40:43]
	v_mfma_f32_16x16x32_bf16 v[0:3], v[180:183], v[144:147], v[0:3]
